# v13 plus attention tile loop stagger: waves 4-7 stage the next K/V tile at the end of the tile instead of the start
# baseline (speedup 1.0000x reference)
; #define AT_LOADN(i_) do { const unsigned char* zt_ = (const unsigned char*)(z0 + (size_t)(b * SEQ + 64 * (i_) - 256) * AB_Z); \
;         kreg[0] = *(const GAS v4u*)(zt_ + klo_); kreg[1] = *(const GAS v4u*)(zt_ + klo_ + 16); vreg[0] = *(const GAS v4u*)(zt_ + klo_ + 4096); vreg[1] = *(const GAS v4u*)(zt_ + klo_ + 4112); } while (0)
; __device__ __forceinline__ void attn_item(Frame& F, const Args& A, int b, int h, int j) {
;     ...
;         if (i < imax) { AT_STAGE(buf ^ 1); if (i + 1 < imax) AT_LOADN(i + 2); }
.LBB0_708:
	v_readlane_b32 s98, v247, 42
	s_bitcmp1_b32 s98, 8
	s_cbranch_scc1 .LBB0_712
	s_waitcnt vmcnt(2)
	v_lshlrev_b32_e32 v120, 16, v34
	v_and_b32_e32 v121, 0xffff0000, v34
	s_waitcnt vmcnt(1)
	v_lshlrev_b32_e32 v128, 16, v38
	v_and_b32_e32 v129, 0xffff0000, v38
	v_mul_f32_e32 v120, v120, v120
	v_mul_f32_e32 v121, v121, v121
	v_lshlrev_b32_e32 v122, 16, v35
	v_fmac_f32_e32 v120, v128, v128
	v_fmac_f32_e32 v121, v129, v129
	v_lshlrev_b32_e32 v130, 16, v39
	v_add_f32_e32 v120, v120, v121
	v_mul_f32_e32 v121, v122, v122
	v_and_b32_e32 v123, 0xffff0000, v35
	v_fmac_f32_e32 v121, v130, v130
	v_and_b32_e32 v131, 0xffff0000, v39
	v_add_f32_e32 v120, v121, v120
	v_mul_f32_e32 v121, v123, v123
	v_lshlrev_b32_e32 v124, 16, v36
	v_fmac_f32_e32 v121, v131, v131
	v_lshlrev_b32_e32 v132, 16, v40
	v_add_f32_e32 v120, v121, v120
	v_mul_f32_e32 v121, v124, v124
	v_and_b32_e32 v125, 0xffff0000, v36
	v_fmac_f32_e32 v121, v132, v132
	v_and_b32_e32 v133, 0xffff0000, v40
	v_add_f32_e32 v120, v121, v120
	v_mul_f32_e32 v121, v125, v125
	v_lshlrev_b32_e32 v126, 16, v37
	v_fmac_f32_e32 v121, v133, v133
	v_lshlrev_b32_e32 v134, 16, v41
	v_add_f32_e32 v120, v121, v120
	v_mul_f32_e32 v121, v126, v126
	v_and_b32_e32 v127, 0xffff0000, v37
	v_fmac_f32_e32 v121, v134, v134
	v_and_b32_e32 v135, 0xffff0000, v41
	v_add_f32_e32 v120, v121, v120
	v_mul_f32_e32 v121, v127, v127
	v_fmac_f32_e32 v121, v135, v135
	v_add_f32_e32 v120, v121, v120
	s_nop 1
	v_add_f32_dpp v120, v120, v120 quad_perm:[1,0,3,2] row_mask:0xf bank_mask:0xf bound_ctrl:1
	s_nop 1
	v_add_f32_dpp v120, v120, v120 quad_perm:[2,3,0,1] row_mask:0xf bank_mask:0xf bound_ctrl:1
	s_nop 1
	v_mov_b32_dpp v121, v120 row_half_mirror row_mask:0xf bank_mask:0xf bound_ctrl:1
	s_and_saveexec_b64 s[4:5], s[2:3]
	s_cbranch_execz .LBB0_710
	v_add_f32_e32 v120, v120, v121
	v_fmamk_f32 v120, v120, 0x3c000000, v163
	v_rsq_f32_e32 v120, v120
	s_lshl_b32 s8, s6, 8
	s_xor_b32 s8, s8, 0x100
	v_add_u32_e32 v121, s8, v147
	ds_write_b32 v121, v120

; #define AT_LOADN(i_) do { const unsigned char* zt_ = (const unsigned char*)(z0 + (size_t)(b * SEQ + 64 * (i_) - 256) * AB_Z); \
;         kreg[0] = *(const GAS v4u*)(zt_ + klo_); kreg[1] = *(const GAS v4u*)(zt_ + klo_ + 16); vreg[0] = *(const GAS v4u*)(zt_ + klo_ + 4096); vreg[1] = *(const GAS v4u*)(zt_ + klo_ + 4112); } while (0)
; __device__ __forceinline__ void attn_item(Frame& F, const Args& A, int b, int h, int j) {
;     ...
;     const unsigned klo_ = (unsigned)(skey * AB_Z + 6144 + 128 * h + sdc) * 2u;
;     ...
;         if (i < imax) { AT_STAGE(buf ^ 1); if (i + 1 < imax) AT_LOADN(i + 2); }
.LBB0_723:
	v_readlane_b32 s98, v247, 42
	s_bitcmp1_b32 s98, 8
	s_cbranch_scc0 .Lst_done
	s_add_i32 s100, s66, 0x44
	s_cmp_ge_i32 s100, s74
	s_cbranch_scc1 .Lst_done
	s_and_b32 s99, s100, 1
	s_waitcnt vmcnt(2)
	v_lshlrev_b32_e32 v120, 16, v34
	v_and_b32_e32 v121, 0xffff0000, v34
	s_waitcnt vmcnt(1)
	v_lshlrev_b32_e32 v128, 16, v38
	v_and_b32_e32 v129, 0xffff0000, v38
	v_mul_f32_e32 v120, v120, v120
	v_mul_f32_e32 v121, v121, v121
	v_lshlrev_b32_e32 v122, 16, v35
	v_fmac_f32_e32 v120, v128, v128
	v_fmac_f32_e32 v121, v129, v129
	v_lshlrev_b32_e32 v130, 16, v39
	v_add_f32_e32 v120, v120, v121
	v_mul_f32_e32 v121, v122, v122
	v_and_b32_e32 v123, 0xffff0000, v35
	v_fmac_f32_e32 v121, v130, v130
	v_and_b32_e32 v131, 0xffff0000, v39
	v_add_f32_e32 v120, v121, v120
	v_mul_f32_e32 v121, v123, v123
	v_lshlrev_b32_e32 v124, 16, v36
	v_fmac_f32_e32 v121, v131, v131
	v_lshlrev_b32_e32 v132, 16, v40
	v_add_f32_e32 v120, v121, v120
	v_mul_f32_e32 v121, v124, v124
	v_and_b32_e32 v125, 0xffff0000, v36
	v_fmac_f32_e32 v121, v132, v132
	v_and_b32_e32 v133, 0xffff0000, v40
	v_add_f32_e32 v120, v121, v120
	v_mul_f32_e32 v121, v125, v125
	v_lshlrev_b32_e32 v126, 16, v37
	v_fmac_f32_e32 v121, v133, v133
	v_lshlrev_b32_e32 v134, 16, v41
	v_add_f32_e32 v120, v121, v120
	v_mul_f32_e32 v121, v126, v126
	v_and_b32_e32 v127, 0xffff0000, v37
	v_fmac_f32_e32 v121, v134, v134
	v_and_b32_e32 v135, 0xffff0000, v41
	v_add_f32_e32 v120, v121, v120
	v_mul_f32_e32 v121, v127, v127
	v_fmac_f32_e32 v121, v135, v135
	v_add_f32_e32 v120, v121, v120
	s_nop 1
	v_add_f32_dpp v120, v120, v120 quad_perm:[1,0,3,2] row_mask:0xf bank_mask:0xf bound_ctrl:1
	s_nop 1
	v_add_f32_dpp v120, v120, v120 quad_perm:[2,3,0,1] row_mask:0xf bank_mask:0xf bound_ctrl:1
	s_nop 1
	v_mov_b32_dpp v121, v120 row_half_mirror row_mask:0xf bank_mask:0xf bound_ctrl:1
	s_and_saveexec_b64 s[4:5], s[2:3]
	s_cbranch_execz .Lst_710
	v_add_f32_e32 v120, v120, v121
	v_fmamk_f32 v120, v120, 0x3c000000, v163
	v_rsq_f32_e32 v120, v120
	s_lshl_b32 s8, s99, 8
	s_xor_b32 s8, s8, 0x100
	v_add_u32_e32 v121, s8, v147
	ds_write_b32 v121, v120
.Lst_710:
	s_or_b64 exec, exec, s[4:5]
	s_xor_b32 s4, s99, 1
	s_mulk_i32 s4, 0x4800
	v_add_u32_e32 v120, s4, v171
	s_cmp_ge_i32 s100, s86
	ds_write_b128 v120, v[34:37]
	ds_write_b128 v120, v[38:41] offset:16
	ds_write_b128 v120, v[42:45] offset:36864
	s_waitcnt vmcnt(0)
	ds_write_b128 v120, v[46:49] offset:36880
	s_cbranch_scc1 .Lst_done
	s_add_i32 s4, s70, s64
	s_addk_i32 s4, 0xff41
	v_mad_i64_i32 v[42:43], s[4:5], s4, v169, v[150:151]
	s_mov_b64 s[4:5], 0x1000
	global_load_dwordx4 v[38:41], v[42:43], off offset:16
	global_load_dwordx4 v[34:37], v[42:43], off
	v_lshl_add_u64 v[46:47], v[42:43], 0, s[4:5]
	v_add_co_u32_e32 v42, vcc, 0x1000, v42
	s_nop 1
	v_addc_co_u32_e32 v43, vcc, 0, v43, vcc
	global_load_dwordx4 v[42:45], v[42:43], off
	s_nop 0
	global_load_dwordx4 v[46:49], v[46:47], off offset:16
